# Griffin conv inputs: 67 unique rows fetched once with coalesced loads, staged in LDS at the latch, read into the tap registers (replaces 16 strided dwordx4 loads + 64 v_mov per thread per tile)
# speedup vs baseline: 1.0249x; 1.0052x over previous
.LBB0_481:
	s_or_b64 exec, exec, s[14:15]
	s_lshl_b32 s16, s16, 2
	v_lshl_add_u64 v[4:5], v[150:151], 0, s[16:17]
	v_lshl_add_u64 v[2:3], v[152:153], 0, s[16:17]
	v_lshl_add_u64 v[4:5], v[4:5], 0, s[20:21]
	v_cndmask_b32_e64 v3, v5, v3, s[10:11]
	v_cndmask_b32_e64 v2, v4, v2, s[10:11]
	s_lshl_b32 s16, s27, 14
	v_lshl_add_u64 v[2:3], v[2:3], 0, s[16:17]
	v_mov_b32_e32 v155, v149
	v_lshl_add_u64 v[2:3], v[2:3], 0, v[154:155]
	s_waitcnt lgkmcnt(0)
	s_barrier
	global_load_dword v4, v[2:3], off offset:512
	global_load_dword v5, v[2:3], off
	global_load_dword v6, v[2:3], off offset:768
	global_load_dword v7, v[2:3], off offset:256
	global_load_dword v8, v[2:3], off offset:1536
	global_load_dword v9, v[2:3], off offset:1024
	global_load_dword v10, v[2:3], off offset:1792
	s_nop 0
	global_load_dword v2, v[2:3], off offset:1280
	s_ashr_i32 s28, s23, 5
	s_ashr_i32 s29, s28, 31
	v_cmp_eq_u32_e64 s[14:15], s22, v227
	s_lshl_b64 s[22:23], s[28:29], 12
	s_lshl_b64 s[28:29], s[28:29], 23
	s_add_u32 s27, s40, s28
	s_addc_u32 s29, s41, s29
	s_lshl_b32 s24, s24, 2
	s_add_u32 s28, s27, s24
	s_addc_u32 s29, s29, 0
	s_lshl_b32 s24, s25, 4
	v_or_b32_e32 v3, s24, v232
	s_lshl_b32 s26, s26, 1
	v_or_b32_e32 v11, s24, v238
	v_mul_lo_u32 v3, v3, s3
	s_add_u32 s24, s56, s26
	v_mul_lo_u32 v11, v11, s44
	v_add_u32_e32 v148, v236, v3
	s_addc_u32 s25, s57, 0
	v_add_u32_e32 v155, v234, v11
	v_mov_b32_e32 v157, v149
	v_mov_b32_e32 v160, 0
	s_add_u32 s26, s84, s26
	s_mov_b32 s16, -1
	v_mov_b32_e32 v161, v160
	v_mov_b32_e32 v162, v160
	v_mov_b32_e32 v163, v160
	v_mov_b32_e32 v164, v160
	v_mov_b32_e32 v165, v160
	v_mov_b32_e32 v166, v160
	v_mov_b32_e32 v167, v160
	v_mov_b32_e32 v168, v160
	v_mov_b32_e32 v169, v160
	v_mov_b32_e32 v170, v160
	v_mov_b32_e32 v171, v160
	v_mov_b32_e32 v172, v160
	v_mov_b32_e32 v173, v160
	v_mov_b32_e32 v176, v160
	v_mov_b32_e32 v177, v160
	v_mov_b32_e32 v174, v160
	v_lshlrev_b32_e32 v158, 11, v233
	v_lshl_add_u32 v158, v232, 4, v158
	v_mov_b32_e32 v159, 0
	v_lshl_add_u64 v[158:159], s[28:29], 0, v[158:159]
	s_addc_u32 s27, s85, 0
	v_mov_b32_e32 v175, v160
	v_mov_b32_e32 v178, v160
	v_mov_b32_e32 v179, v160
	v_mov_b32_e32 v180, v160
	v_mov_b32_e32 v181, v160
	v_mov_b32_e32 v182, v160
	v_mov_b32_e32 v183, v160
	v_mov_b32_e32 v184, v160
	v_mov_b32_e32 v185, v160
	v_mov_b32_e32 v186, v160
	v_mov_b32_e32 v187, v160
	v_mov_b32_e32 v188, v160
	v_mov_b32_e32 v189, v160
	v_mov_b32_e32 v192, v160
	v_mov_b32_e32 v193, v160
	v_mov_b32_e32 v190, v160
	v_mov_b32_e32 v191, v160
	v_mov_b32_e32 v194, v160
	v_mov_b32_e32 v195, v160
	v_mov_b32_e32 v196, v160
	v_mov_b32_e32 v197, v160
	v_mov_b32_e32 v198, v160
	v_mov_b32_e32 v199, v160
	v_mov_b32_e32 v200, v160
	v_mov_b32_e32 v201, v160
	v_mov_b32_e32 v202, v160
	v_mov_b32_e32 v203, v160
	v_mov_b32_e32 v204, v160
	v_mov_b32_e32 v205, v160
	v_mov_b32_e32 v208, v160
	s_waitcnt vmcnt(7)
	v_and_b32_sdwa v3, v4, v248 dst_sel:DWORD dst_unused:UNUSED_PAD src0_sel:WORD_1 src1_sel:DWORD
	s_waitcnt vmcnt(6)
	v_and_b32_sdwa v11, v5, v248 dst_sel:DWORD dst_unused:UNUSED_PAD src0_sel:WORD_1 src1_sel:DWORD
	s_waitcnt vmcnt(5)
	v_and_b32_sdwa v12, v6, v248 dst_sel:DWORD dst_unused:UNUSED_PAD src0_sel:WORD_1 src1_sel:DWORD
	s_waitcnt vmcnt(4)
	v_and_b32_sdwa v13, v7, v248 dst_sel:DWORD dst_unused:UNUSED_PAD src0_sel:WORD_1 src1_sel:DWORD
	s_waitcnt vmcnt(3)
	v_and_b32_sdwa v14, v8, v248 dst_sel:DWORD dst_unused:UNUSED_PAD src0_sel:WORD_1 src1_sel:DWORD
	s_waitcnt vmcnt(2)
	v_and_b32_sdwa v15, v9, v248 dst_sel:DWORD dst_unused:UNUSED_PAD src0_sel:WORD_1 src1_sel:DWORD
	s_waitcnt vmcnt(1)
	v_and_b32_sdwa v16, v10, v248 dst_sel:DWORD dst_unused:UNUSED_PAD src0_sel:WORD_1 src1_sel:DWORD
	s_waitcnt vmcnt(0)
	v_and_b32_sdwa v17, v2, v248 dst_sel:DWORD dst_unused:UNUSED_PAD src0_sel:WORD_1 src1_sel:DWORD
	v_add3_u32 v3, v4, v3, s43
	v_add3_u32 v4, v6, v12, s43
	v_add3_u32 v6, v7, v13, s43
	v_add3_u32 v7, v9, v15, s43
	v_add3_u32 v9, v10, v16, s43
	v_add3_u32 v2, v2, v17, s43
	v_add3_u32 v5, v5, v11, s43
	v_add3_u32 v8, v8, v14, s43
	v_and_b32_e32 v4, 0xffff0000, v4
	v_and_b32_e32 v6, 0xffff0000, v6
	v_and_b32_e32 v9, 0xffff0000, v9
	v_and_b32_e32 v10, 0xffff0000, v2
	v_or_b32_sdwa v3, v4, v3 dst_sel:DWORD dst_unused:UNUSED_PAD src0_sel:DWORD src1_sel:WORD_1
	v_or_b32_sdwa v2, v6, v5 dst_sel:DWORD dst_unused:UNUSED_PAD src0_sel:DWORD src1_sel:WORD_1
	v_or_b32_sdwa v5, v9, v8 dst_sel:DWORD dst_unused:UNUSED_PAD src0_sel:DWORD src1_sel:WORD_1
	v_or_b32_sdwa v4, v10, v7 dst_sel:DWORD dst_unused:UNUSED_PAD src0_sel:DWORD src1_sel:WORD_1
	v_mov_b32_e32 v209, v160
	v_mov_b32_e32 v206, v160
	v_mov_b32_e32 v207, v160
	v_mov_b32_e32 v210, v160
	v_mov_b32_e32 v211, v160
	v_mov_b32_e32 v212, v160
	v_mov_b32_e32 v213, v160
	v_mov_b32_e32 v214, v160
	v_mov_b32_e32 v215, v160
	v_mov_b32_e32 v216, v160
	v_mov_b32_e32 v217, v160
	v_mov_b32_e32 v218, v160
	v_mov_b32_e32 v219, v160
	v_mov_b32_e32 v220, v160
	v_mov_b32_e32 v221, v160
	v_mov_b32_e32 v222, v160
	v_mov_b32_e32 v223, v160
	ds_write_b128 v231, v[2:5] offset:42640
	s_waitcnt lgkmcnt(0)
	s_barrier
	s_branch .LBB0_484

.Lgr_latch_common:
	s_cmp_eq_u32 s45, 64
	s_mov_b32 s16, s45
	v_mul_u32_u24_e32 v224, 0x110, v233
	v_lshl_add_u32 v224, v232, 4, v224
	ds_write_b128 v224, v[2:5] offset:47360
	ds_write_b128 v224, v[6:9] offset:51712
	ds_write_b128 v224, v[10:13] offset:56064
	ds_write_b128 v224, v[14:17] offset:60416
	v_cmp_gt_u32_e32 vcc, 3, v233
	s_and_saveexec_b64 s[28:29], vcc
	s_cbranch_execz .Lgx_skipw5
	ds_write_b128 v224, v[18:21] offset:64768
.Lgx_skipw5:
	s_or_b64 exec, exec, s[28:29]
	s_waitcnt lgkmcnt(0)
	s_barrier
	v_mul_u32_u24_e32 v224, 0x110, v228
	v_and_b32_e32 v225, 3, v232
	v_lshl_add_u32 v224, v225, 6, v224
	ds_read_b64 v[160:161], v224 offset:47360
	ds_read_b64 v[162:163], v224 offset:47632
	ds_read_b64 v[164:165], v224 offset:47904
	ds_read_b64 v[166:167], v224 offset:48176
	ds_read_b64 v[168:169], v224 offset:47368
	ds_read_b64 v[170:171], v224 offset:47640
	ds_read_b64 v[172:173], v224 offset:47912
	ds_read_b64 v[174:175], v224 offset:47376
	ds_read_b64 v[176:177], v224 offset:48184
	ds_read_b64 v[178:179], v224 offset:47648
	ds_read_b64 v[180:181], v224 offset:47920
	ds_read_b64 v[182:183], v224 offset:48192
	s_waitcnt lgkmcnt(0)
	ds_read_b64 v[184:185], v224 offset:47384
	ds_read_b64 v[186:187], v224 offset:47656
	ds_read_b64 v[188:189], v224 offset:47928
	ds_read_b64 v[190:191], v224 offset:47392
	ds_read_b64 v[192:193], v224 offset:48200
	ds_read_b64 v[194:195], v224 offset:47664
	ds_read_b64 v[196:197], v224 offset:47936
	ds_read_b64 v[198:199], v224 offset:48208
	ds_read_b64 v[200:201], v224 offset:47400
	ds_read_b64 v[202:203], v224 offset:47672
	ds_read_b64 v[204:205], v224 offset:47944
	ds_read_b64 v[206:207], v224 offset:47408
	s_waitcnt lgkmcnt(0)
	ds_read_b64 v[208:209], v224 offset:48216
	ds_read_b64 v[210:211], v224 offset:47680
	ds_read_b64 v[212:213], v224 offset:47952
	ds_read_b64 v[214:215], v224 offset:48224
	ds_read_b64 v[216:217], v224 offset:47416
	ds_read_b64 v[218:219], v224 offset:47688
	ds_read_b64 v[220:221], v224 offset:47960
	ds_read_b64 v[222:223], v224 offset:48232
	s_waitcnt lgkmcnt(0)
	s_cmp_eq_u32 s45, 64
	s_cbranch_scc1 .LBB0_470

.LBB0_486:
	s_waitcnt lgkmcnt(14)
	ds_read_b128 v[126:129], v235 offset:8320
	ds_read_b128 v[94:97], v235 offset:8336
	ds_read_b128 v[74:77], v235 offset:8352
	ds_read_b128 v[66:69], v235 offset:8368
	ds_read_b128 v[130:133], v235 offset:9344
	ds_read_b128 v[110:113], v235 offset:9360
	s_waitcnt lgkmcnt(14)
	ds_read_b128 v[134:137], v235 offset:8576
	ds_read_b128 v[114:117], v235 offset:8592
	ds_read_b128 v[138:141], v235 offset:8832
	ds_read_b128 v[118:121], v235 offset:8848
	ds_read_b128 v[142:145], v235 offset:9088
	ds_read_b128 v[122:125], v235 offset:9104
	s_waitcnt lgkmcnt(14)
	ds_read_b128 v[90:93], v235 offset:9376
	ds_read_b128 v[70:73], v235 offset:9392
	ds_read_b128 v[98:101], v235 offset:8608
	ds_read_b128 v[78:81], v235 offset:8624
	ds_read_b128 v[102:105], v235 offset:8864
	ds_read_b128 v[82:85], v235 offset:8880
	s_waitcnt lgkmcnt(14)
	ds_read_b128 v[106:109], v235 offset:9120
	ds_read_b128 v[86:89], v235 offset:9136
	s_add_i32 s45, s16, 1
	s_cmp_eq_u32 s16, 63
	v_mov_b32_e32 v53, v223
	v_mov_b32_e32 v52, v222
	v_mov_b32_e32 v37, v221
	v_mov_b32_e32 v36, v220
	v_mov_b32_e32 v21, v219
	v_mov_b32_e32 v20, v218
	v_mov_b32_e32 v5, v217
	v_mov_b32_e32 v4, v216
	v_mov_b32_e32 v51, v215
	v_mov_b32_e32 v50, v214
	v_mov_b32_e32 v35, v213
	v_mov_b32_e32 v34, v212
	v_mov_b32_e32 v19, v211
	v_mov_b32_e32 v18, v210
	v_mov_b32_e32 v3, v207
	v_mov_b32_e32 v2, v206
	v_mov_b32_e32 v61, v209
	v_mov_b32_e32 v60, v208
	v_mov_b32_e32 v45, v205
	v_mov_b32_e32 v44, v204
	v_mov_b32_e32 v29, v203
	v_mov_b32_e32 v28, v202
	v_mov_b32_e32 v13, v201
	v_mov_b32_e32 v12, v200
	v_mov_b32_e32 v59, v199
	v_mov_b32_e32 v58, v198
	v_mov_b32_e32 v43, v197
	v_mov_b32_e32 v42, v196
	v_mov_b32_e32 v27, v195
	v_mov_b32_e32 v26, v194
	v_mov_b32_e32 v11, v191
	v_mov_b32_e32 v10, v190
	v_mov_b32_e32 v57, v193
	v_mov_b32_e32 v56, v192
	v_mov_b32_e32 v41, v189
	v_mov_b32_e32 v40, v188
	v_mov_b32_e32 v25, v187
	v_mov_b32_e32 v24, v186
	v_mov_b32_e32 v9, v185
	v_mov_b32_e32 v8, v184
	v_mov_b32_e32 v55, v183
	v_mov_b32_e32 v54, v182
	v_mov_b32_e32 v39, v181
	v_mov_b32_e32 v38, v180
	v_mov_b32_e32 v23, v179
	v_mov_b32_e32 v22, v178
	v_mov_b32_e32 v7, v175
	v_mov_b32_e32 v6, v174
	v_mov_b32_e32 v65, v177
	v_mov_b32_e32 v64, v176
	v_mov_b32_e32 v49, v173
	v_mov_b32_e32 v48, v172
	v_mov_b32_e32 v33, v171
	v_mov_b32_e32 v32, v170
	v_mov_b32_e32 v17, v169
	v_mov_b32_e32 v16, v168
	v_mov_b32_e32 v63, v167
	v_mov_b32_e32 v62, v166
	v_mov_b32_e32 v47, v165
	v_mov_b32_e32 v46, v164
	v_mov_b32_e32 v31, v163
	v_mov_b32_e32 v30, v162
	v_mov_b32_e32 v15, v161
	v_mov_b32_e32 v14, v160
	s_cbranch_scc1 .LBB0_520
	s_lshl_b32 s28, s45, 6
	s_add_i32 s28, s28, -3
	s_ashr_i32 s29, s28, 31
	s_lshl_b64 s[28:29], s[28:29], 11
	v_lshl_add_u64 v[224:225], v[158:159], 0, s[28:29]
	s_cmp_lg_u32 s45, 0
	s_cselect_b64 s[28:29], -1, 0
	v_cmp_lt_u32_e32 vcc, 2, v233
	v_mov_b32_e32 v2, 0
	v_mov_b32_e32 v3, 0
	v_mov_b32_e32 v4, 0
	v_mov_b32_e32 v5, 0
	s_or_b64 s[28:29], s[28:29], vcc
	s_mov_b32 s30, 0x8000
	s_mov_b32 s31, 0
	s_and_saveexec_b64 s[34:35], s[28:29]
	s_cbranch_execz .Lgx_l0
	global_load_dwordx4 v[2:5], v[224:225], off
.Lgx_l0:
	s_or_b64 exec, exec, s[34:35]
	v_lshl_add_u64 v[224:225], v[224:225], 0, s[30:31]
	global_load_dwordx4 v[6:9], v[224:225], off
	v_lshl_add_u64 v[224:225], v[224:225], 0, s[30:31]
	global_load_dwordx4 v[10:13], v[224:225], off
	v_lshl_add_u64 v[224:225], v[224:225], 0, s[30:31]
	global_load_dwordx4 v[14:17], v[224:225], off
	v_lshl_add_u64 v[224:225], v[224:225], 0, s[30:31]
	v_cmp_gt_u32_e32 vcc, 3, v233
	s_and_saveexec_b64 s[34:35], vcc
	s_cbranch_execz .Lgx_skip5
	global_load_dwordx4 v[18:21], v[224:225], off
.Lgx_skip5:
	s_or_b64 exec, exec, s[34:35]
.LBB0_520:
	s_cmp_lt_i32 s16, 0
	s_cbranch_scc1 .LBB0_483
	s_waitcnt lgkmcnt(14)
	v_pk_fma_f32 v[126:127], v[160:161], v[126:127], v[130:131]
	v_pk_fma_f32 v[128:129], v[168:169], v[128:129], v[132:133]
	s_waitcnt lgkmcnt(13)
	v_pk_fma_f32 v[126:127], v[162:163], v[134:135], v[126:127]
	v_pk_fma_f32 v[128:129], v[170:171], v[136:137], v[128:129]
	s_waitcnt lgkmcnt(11)
	v_pk_fma_f32 v[126:127], v[164:165], v[138:139], v[126:127]
	v_pk_fma_f32 v[128:129], v[172:173], v[140:141], v[128:129]
	v_pk_fma_f32 v[94:95], v[174:175], v[94:95], v[110:111]
	v_pk_fma_f32 v[96:97], v[184:185], v[96:97], v[112:113]
	s_waitcnt lgkmcnt(9)
	v_pk_fma_f32 v[126:127], v[166:167], v[142:143], v[126:127]
	v_pk_fma_f32 v[128:129], v[176:177], v[144:145], v[128:129]
	v_pk_fma_f32 v[94:95], v[178:179], v[114:115], v[94:95]
	v_pk_fma_f32 v[96:97], v[186:187], v[116:117], v[96:97]
	s_waitcnt lgkmcnt(6)
	v_pk_fma_f32 v[66:67], v[206:207], v[66:67], v[70:71]
	v_pk_fma_f32 v[68:69], v[216:217], v[68:69], v[72:73]
	v_pk_fma_f32 v[94:95], v[180:181], v[118:119], v[94:95]
	v_pk_fma_f32 v[96:97], v[188:189], v[120:121], v[96:97]
	s_waitcnt lgkmcnt(4)
	v_pk_fma_f32 v[66:67], v[210:211], v[78:79], v[66:67]
	v_pk_fma_f32 v[68:69], v[218:219], v[80:81], v[68:69]
	v_and_b32_sdwa v79, v129, v248 dst_sel:DWORD dst_unused:UNUSED_PAD src0_sel:WORD_1 src1_sel:DWORD
	v_and_b32_sdwa v80, v127, v248 dst_sel:DWORD dst_unused:UNUSED_PAD src0_sel:WORD_1 src1_sel:DWORD
	v_pk_fma_f32 v[94:95], v[182:183], v[122:123], v[94:95]
	v_pk_fma_f32 v[96:97], v[192:193], v[124:125], v[96:97]
	v_and_b32_sdwa v73, v128, v248 dst_sel:DWORD dst_unused:UNUSED_PAD src0_sel:WORD_1 src1_sel:DWORD
	v_and_b32_sdwa v78, v126, v248 dst_sel:DWORD dst_unused:UNUSED_PAD src0_sel:WORD_1 src1_sel:DWORD
	v_add3_u32 v79, v129, v79, s43
	v_add3_u32 v80, v127, v80, s43
	v_pk_fma_f32 v[74:75], v[190:191], v[74:75], v[90:91]
	v_pk_fma_f32 v[76:77], v[200:201], v[76:77], v[92:93]
	s_waitcnt lgkmcnt(2)
	v_pk_fma_f32 v[66:67], v[212:213], v[82:83], v[66:67]
	v_add3_u32 v78, v126, v78, s43
	v_add3_u32 v73, v128, v73, s43
	v_and_b32_e32 v79, 0xffff0000, v79
	v_and_b32_e32 v80, 0xffff0000, v80
	v_and_b32_sdwa v81, v97, v248 dst_sel:DWORD dst_unused:UNUSED_PAD src0_sel:WORD_1 src1_sel:DWORD
	v_and_b32_sdwa v82, v95, v248 dst_sel:DWORD dst_unused:UNUSED_PAD src0_sel:WORD_1 src1_sel:DWORD
	v_pk_fma_f32 v[74:75], v[194:195], v[98:99], v[74:75]
	v_pk_fma_f32 v[76:77], v[202:203], v[100:101], v[76:77]
	v_mov_b32_e32 v71, v227
	v_mov_b32_e32 v70, v228
	v_or_b32_sdwa v79, v79, v73 dst_sel:DWORD dst_unused:UNUSED_PAD src0_sel:DWORD src1_sel:WORD_1
	v_or_b32_sdwa v78, v80, v78 dst_sel:DWORD dst_unused:UNUSED_PAD src0_sel:DWORD src1_sel:WORD_1
	v_and_b32_sdwa v73, v96, v248 dst_sel:DWORD dst_unused:UNUSED_PAD src0_sel:WORD_1 src1_sel:DWORD
	v_and_b32_sdwa v80, v94, v248 dst_sel:DWORD dst_unused:UNUSED_PAD src0_sel:WORD_1 src1_sel:DWORD
	v_add3_u32 v81, v97, v81, s43
	v_add3_u32 v82, v95, v82, s43
	v_pk_fma_f32 v[74:75], v[196:197], v[102:103], v[74:75]
	v_pk_fma_f32 v[76:77], v[204:205], v[104:105], v[76:77]
	v_add3_u32 v80, v94, v80, s43
	v_mul_lo_u32 v72, v70, s3
	v_add3_u32 v73, v96, v73, s43
	v_and_b32_e32 v81, 0xffff0000, v81
	v_and_b32_e32 v82, 0xffff0000, v82
	s_waitcnt lgkmcnt(1)
	v_pk_fma_f32 v[74:75], v[198:199], v[106:107], v[74:75]
	v_pk_fma_f32 v[76:77], v[208:209], v[108:109], v[76:77]
	v_lshl_add_u32 v72, v71, 5, v72
	v_or_b32_sdwa v81, v81, v73 dst_sel:DWORD dst_unused:UNUSED_PAD src0_sel:DWORD src1_sel:WORD_1
	v_or_b32_sdwa v80, v82, v80 dst_sel:DWORD dst_unused:UNUSED_PAD src0_sel:DWORD src1_sel:WORD_1
	v_pk_fma_f32 v[68:69], v[220:221], v[84:85], v[68:69]
	ds_write_b128 v72, v[78:81] offset:33424
	v_and_b32_sdwa v79, v77, v248 dst_sel:DWORD dst_unused:UNUSED_PAD src0_sel:WORD_1 src1_sel:DWORD
	v_and_b32_sdwa v80, v75, v248 dst_sel:DWORD dst_unused:UNUSED_PAD src0_sel:WORD_1 src1_sel:DWORD
	s_waitcnt lgkmcnt(1)
	v_pk_fma_f32 v[66:67], v[214:215], v[86:87], v[66:67]
	v_pk_fma_f32 v[68:69], v[222:223], v[88:89], v[68:69]
	v_and_b32_sdwa v73, v76, v248 dst_sel:DWORD dst_unused:UNUSED_PAD src0_sel:WORD_1 src1_sel:DWORD
	v_and_b32_sdwa v78, v74, v248 dst_sel:DWORD dst_unused:UNUSED_PAD src0_sel:WORD_1 src1_sel:DWORD
	v_add3_u32 v79, v77, v79, s43
	v_add3_u32 v80, v75, v80, s43
	v_add3_u32 v78, v74, v78, s43
	v_add3_u32 v73, v76, v73, s43
	v_and_b32_e32 v79, 0xffff0000, v79
	v_and_b32_e32 v80, 0xffff0000, v80
	v_and_b32_sdwa v81, v69, v248 dst_sel:DWORD dst_unused:UNUSED_PAD src0_sel:WORD_1 src1_sel:DWORD
	v_and_b32_sdwa v82, v67, v248 dst_sel:DWORD dst_unused:UNUSED_PAD src0_sel:WORD_1 src1_sel:DWORD
	v_or_b32_sdwa v79, v79, v73 dst_sel:DWORD dst_unused:UNUSED_PAD src0_sel:DWORD src1_sel:WORD_1
	v_or_b32_sdwa v78, v80, v78 dst_sel:DWORD dst_unused:UNUSED_PAD src0_sel:DWORD src1_sel:WORD_1
	v_and_b32_sdwa v73, v68, v248 dst_sel:DWORD dst_unused:UNUSED_PAD src0_sel:WORD_1 src1_sel:DWORD
	v_and_b32_sdwa v80, v66, v248 dst_sel:DWORD dst_unused:UNUSED_PAD src0_sel:WORD_1 src1_sel:DWORD
	v_add3_u32 v81, v69, v81, s43
	v_add3_u32 v82, v67, v82, s43
	v_add3_u32 v80, v66, v80, s43
	v_add3_u32 v73, v68, v73, s43
	v_and_b32_e32 v81, 0xffff0000, v81
	v_and_b32_e32 v82, 0xffff0000, v82
	v_or_b32_sdwa v81, v81, v73 dst_sel:DWORD dst_unused:UNUSED_PAD src0_sel:DWORD src1_sel:WORD_1
	v_or_b32_sdwa v80, v82, v80 dst_sel:DWORD dst_unused:UNUSED_PAD src0_sel:DWORD src1_sel:WORD_1
	ds_write_b128 v72, v[78:81] offset:33440
	s_and_saveexec_b64 s[28:29], s[14:15]
	s_cbranch_execz .LBB0_523
	v_mul_lo_u32 v72, v70, s33
	v_add_u32_e32 v73, 0x7180, v72
	ds_write2_b32 v73, v126, v127 offset1:1
	v_add_u32_e32 v73, 0x7188, v72
	ds_write2_b32 v73, v128, v129 offset1:1
	v_add_u32_e32 v73, 0x7190, v72
	ds_write2_b32 v73, v94, v95 offset1:1
	v_add_u32_e32 v73, 0x7198, v72
	ds_write2_b32 v73, v96, v97 offset1:1
	v_add_u32_e32 v73, 0x71a0, v72
	ds_write2_b32 v73, v74, v75 offset1:1
	v_add_u32_e32 v73, 0x71a8, v72
	ds_write2_b32 v73, v76, v77 offset1:1
	v_add_u32_e32 v73, 0x71b0, v72
	ds_write2_b32 v73, v66, v67 offset1:1
	v_add_u32_e32 v66, 0x71b8, v72
	ds_write2_b32 v66, v68, v69 offset1:1
